# P0 barrier instance gets the same three-deep poll, immediate invalidate on hit and back-to-back release atomics as the layer-loop instances
# baseline (speedup 1.0000x reference)
; __device__ __forceinline__ unsigned xb_add(unsigned* p, unsigned v) { return __hip_atomic_fetch_add(p, v, __ATOMIC_RELAXED, __HIP_MEMORY_SCOPE_AGENT); }
; __device__ __forceinline__ void xcd_barrier(const XcdBarrier& b) {
;     ...
;         const unsigned old = xb_add(&bar[XB_XSUB(bx_)], 1u);
;         const unsigned gen = old / nloc;
;         if (old + 1u == (gen + 1u) * nloc) {
;             __builtin_amdgcn_fence(__ATOMIC_RELEASE, "agent");
;             asm volatile("s_waitcnt vmcnt(0)" ::: "memory");
; #pragma unroll
;             for (unsigned j = 0; j < 16; ++j) if ((xmask >> j) & 1u) (void)xb_add(&bar[XB_XGEN(j)], 1u);
.LBB0_130:
	s_lshl_b32 s6, s33, 6
	s_add_i32 s2, s6, 0x500
	s_mov_b32 s3, 0
	s_lshl_b64 s[2:3], s[2:3], 2
	s_add_u32 s2, s36, s2
	s_addc_u32 s3, s37, s3
	v_mov_b32_e32 v3, 1
	v_mov_b64_e32 v[6:7], s[2:3]
	flat_atomic_add v3, v[6:7], v3 sc0
	v_cvt_f32_u32_e32 v5, v4
	v_sub_u32_e32 v6, 0, v4
	v_rcp_iflag_f32_e32 v5, v5
	s_nop 0
	v_mul_f32_e32 v5, 0x4f7ffffe, v5
	v_cvt_u32_f32_e32 v5, v5
	v_mul_lo_u32 v6, v6, v5
	v_mul_hi_u32 v6, v5, v6
	v_add_u32_e32 v5, v5, v6
	s_waitcnt vmcnt(0) lgkmcnt(0)
	v_mul_hi_u32 v5, v3, v5
	v_mul_lo_u32 v6, v5, v4
	v_sub_u32_e32 v6, v3, v6
	v_add_u32_e32 v7, 1, v5
	v_cmp_ge_u32_e32 vcc, v6, v4
	s_nop 1
	v_cndmask_b32_e32 v5, v5, v7, vcc
	v_sub_u32_e32 v7, v6, v4
	v_cndmask_b32_e32 v6, v6, v7, vcc
	v_add_u32_e32 v7, 1, v5
	v_cmp_ge_u32_e32 vcc, v6, v4
	v_add_u32_e32 v6, 1, v3
	s_nop 0
	v_cndmask_b32_e32 v5, v5, v7, vcc
	v_add_u32_e32 v3, 1, v5
	v_mul_lo_u32 v4, v3, v4
	v_cmp_eq_u32_e32 vcc, v6, v4
	s_and_saveexec_b64 s[2:3], vcc
	s_cbranch_execz .LBB0_163
	buffer_wbl2 sc1
	s_waitcnt vmcnt(0)
	v_cmp_eq_u32_e32 vcc, 0xff, v2
	s_cbranch_vccz .Lrfz_slow
	v_mov_b32_e32 v4, s36
	v_add_co_u32_e32 v4, vcc, 0x2000, v4
	v_mov_b32_e32 v5, s37
	s_nop 0
	v_addc_co_u32_e32 v5, vcc, 0, v5, vcc
	v_mov_b32_e32 v6, 1
	global_atomic_add v[4:5], v6, off offset:1024
	global_atomic_add v[4:5], v6, off offset:1280
	global_atomic_add v[4:5], v6, off offset:1536
	global_atomic_add v[4:5], v6, off offset:1792
	global_atomic_add v[4:5], v6, off offset:2048
	global_atomic_add v[4:5], v6, off offset:2304
	global_atomic_add v[4:5], v6, off offset:2560
	global_atomic_add v[4:5], v6, off offset:2816
	s_or_b64 exec, exec, s[2:3]
	s_branch .Lrfz_join
.Lrfz_slow:
	v_and_b32_e32 v4, 1, v2
	v_cmp_eq_u32_e32 vcc, 1, v4
	s_and_saveexec_b64 s[4:5], vcc
	s_cbranch_execz .LBB0_133
	v_mov_b32_e32 v4, s36
	v_add_co_u32_e32 v4, vcc, 0x2000, v4
	v_mov_b32_e32 v5, s37
	s_nop 0
	v_addc_co_u32_e32 v5, vcc, 0, v5, vcc
	v_mov_b32_e32 v6, 1
	flat_atomic_add v[4:5], v6 offset:1024

; __device__ __forceinline__ unsigned xb_ld(unsigned* p)              { return __hip_atomic_load(p, __ATOMIC_RELAXED, __HIP_MEMORY_SCOPE_AGENT); }
; __device__ __forceinline__ unsigned xb_add(unsigned* p, unsigned v) { return __hip_atomic_fetch_add(p, v, __ATOMIC_RELAXED, __HIP_MEMORY_SCOPE_AGENT); }
; #define XB_SPIN(cond, bar) do { unsigned _sp = 0; while (cond) { __builtin_amdgcn_s_sleep(1); \
;     if ((++_sp & 255u) == 0u) { if (xb_ld(&(bar)[XB_TMO])) break; if (_sp > XB_SPIN_CAP) { atomicAdd(&(bar)[XB_TMO], 1u); break; } } } } while (0)
; __device__ __forceinline__ void xcd_barrier(const XcdBarrier& b) {
;     ...
;             for (unsigned j = 0; j < 16; ++j) if ((xmask >> j) & 1u) (void)xb_add(&bar[XB_XGEN(j)], 1u);
;         }
;         XB_SPIN(xb_ld(&bar[XB_XGEN(bx_)]) < (gen + 1u) * nx, bar);
;         __builtin_amdgcn_fence(__ATOMIC_ACQUIRE, "agent");
;         asm volatile("s_waitcnt vmcnt(0)" ::: "memory");
.LBB0_161:
	s_or_b64 exec, exec, s[4:5]
	v_and_b32_e32 v2, 0x8000, v2
	v_cmp_ne_u32_e32 vcc, 0, v2
	s_and_b64 exec, exec, vcc
	s_cbranch_execz .LBB0_163
	v_mov_b32_e32 v2, s36
	v_add_co_u32_e32 v4, vcc, 0x3000, v2
	v_mov_b32_e32 v2, s37
	s_nop 0
	v_addc_co_u32_e32 v5, vcc, 0, v2, vcc
	v_mov_b32_e32 v2, 1
	flat_atomic_add v[4:5], v2 offset:768
.LBB0_163:
	s_or_b64 exec, exec, s[2:3]
	s_waitcnt vmcnt(0) lgkmcnt(0)
.Lrfz_join:
	s_add_i32 s2, s6, 0x900
	s_mov_b32 s3, 0
	s_lshl_b64 s[2:3], s[2:3], 2
	s_add_u32 s4, s36, s2
	s_addc_u32 s5, s37, s3
	v_mov_b64_e32 v[4:5], s[4:5]
	v_mul_lo_u32 v1, v3, v1
	s_movk_i32 s2, 0x1000
	global_load_dword v2, v[4:5], off sc1
	s_sleep 10
	global_load_dword v3, v[4:5], off sc1
	s_sleep 10
	global_load_dword v6, v[4:5], off sc1
.Lppz_loop:
	s_waitcnt vmcnt(2)
	v_cmp_ge_u32_e32 vcc, v2, v1
	s_cbranch_vccnz .Lppz_hit
	global_load_dword v2, v[4:5], off sc1
	s_waitcnt vmcnt(2)
	v_cmp_ge_u32_e32 vcc, v3, v1
	s_cbranch_vccnz .Lppz_hit
	global_load_dword v3, v[4:5], off sc1
	s_waitcnt vmcnt(2)
	v_cmp_ge_u32_e32 vcc, v6, v1
	s_cbranch_vccnz .Lppz_hit
	global_load_dword v6, v[4:5], off sc1
	s_sub_u32 s2, s2, 1
	s_cmp_lg_u32 s2, 0
	s_cbranch_scc1 .Lppz_loop
	s_branch .Lppz_miss

; __device__ __forceinline__ unsigned xb_ld(unsigned* p)              { return __hip_atomic_load(p, __ATOMIC_RELAXED, __HIP_MEMORY_SCOPE_AGENT); }
; #define XB_SPIN(cond, bar) do { unsigned _sp = 0; while (cond) { __builtin_amdgcn_s_sleep(1); \
;     if ((++_sp & 255u) == 0u) { if (xb_ld(&(bar)[XB_TMO])) break; if (_sp > XB_SPIN_CAP) { atomicAdd(&(bar)[XB_TMO], 1u); break; } } } } while (0)
; __device__ __forceinline__ void xcd_barrier(const XcdBarrier& b) {
;     ...
;         XB_SPIN(xb_ld(&bar[XB_XGEN(bx_)]) < (gen + 1u) * nx, bar);
;         __builtin_amdgcn_fence(__ATOMIC_ACQUIRE, "agent");
;         asm volatile("s_waitcnt vmcnt(0)" ::: "memory");
.Lppz_miss:
	flat_load_dword v2, v[4:5] sc1
	s_waitcnt vmcnt(0) lgkmcnt(0)
	v_cmp_lt_u32_e32 vcc, v2, v1
	s_and_saveexec_b64 s[2:3], vcc
	s_cbranch_execz .LBB0_174
	s_mov_b32 s20, 1
	s_mov_b64 s[6:7], 0
	s_branch .LBB0_166
